# GEMM accumulator zeroing at unit starts: v_mov_b64 vN:N+1, 0 on pairs instead of 127 v_mov_b32 copies
# speedup vs baseline: 1.0034x; 1.0034x over previous
; template <class Epi>
; __device__ __forceinline__ void gemm_phase(LAS unsigned char* lds, const Gemm g, const Sched& S, const Epi& E) {
;     ...
;         const bool has_next = S.next(ui + 1, nxt);
;         const char* nA = has_next ? (const char*)g.A + (size_t)S.aoff(nxt) * 2 : cA; const char* nB = has_next ? (const char*)g.Bt + (size_t)S.boff(nxt) * 2 : cB;
;     ...
;         for (int a = 0; a < 2; ++a)
; #pragma unroll
;             for (int b = 0; b < 2; ++b)
; #pragma unroll
;                 for (int m = 0; m < 4; ++m)
; #pragma unroll
;                     for (int n = 0; n < 2; ++n) acc[a][b][m][n] = (f32x4){0.f, 0.f, 0.f, 0.f};
.LBB0_162:
	s_ashr_i32 s21, s20, 31
	s_lshl_b64 s[22:23], s[20:21], 19
	s_add_u32 s22, s13, s22
	s_addc_u32 s23, s52, s23
	s_and_b64 s[24:25], s[8:9], exec
	s_cselect_b32 s21, s23, s41
	s_cselect_b32 s27, s22, s40
	s_ashr_i32 s15, s14, 31
	s_lshl_b64 s[24:25], s[14:15], 19
	s_add_u32 s24, s10, s24
	s_addc_u32 s25, s11, s25
	s_and_b64 s[46:47], s[8:9], exec
	s_cselect_b32 s15, s25, s45
	s_cselect_b32 s64, s24, s44
	s_add_u32 s40, s40, 0x40080
	s_addc_u32 s41, s41, 0
	s_add_u32 s65, s44, 0x100
	v_mov_b32_e32 v8, 0
	s_addc_u32 s66, s45, 0
	s_mov_b32 s67, -2
	v_mov_b32_e32 v9, 0
	v_mov_b64_e32 v[10:11], 0
	v_mov_b64_e32 v[0:1], 0
	v_mov_b64_e32 v[2:3], 0
	v_mov_b64_e32 v[24:25], 0
	v_mov_b64_e32 v[26:27], 0
	v_mov_b64_e32 v[16:17], 0
	v_mov_b64_e32 v[18:19], 0
	v_mov_b64_e32 v[40:41], 0
	v_mov_b64_e32 v[42:43], 0
	v_mov_b64_e32 v[32:33], 0
	v_mov_b64_e32 v[34:35], 0
	v_mov_b64_e32 v[56:57], 0
	v_mov_b64_e32 v[58:59], 0
	v_mov_b64_e32 v[48:49], 0
	v_mov_b64_e32 v[50:51], 0
	v_mov_b64_e32 v[12:13], 0
	v_mov_b64_e32 v[14:15], 0
	v_mov_b64_e32 v[4:5], 0
	v_mov_b64_e32 v[6:7], 0
	v_mov_b64_e32 v[28:29], 0
	v_mov_b64_e32 v[30:31], 0
	v_mov_b64_e32 v[20:21], 0
	v_mov_b64_e32 v[22:23], 0
	v_mov_b64_e32 v[44:45], 0
	v_mov_b64_e32 v[46:47], 0
	v_mov_b64_e32 v[36:37], 0
	v_mov_b64_e32 v[38:39], 0
	v_mov_b64_e32 v[60:61], 0
	v_mov_b64_e32 v[62:63], 0
	v_mov_b64_e32 v[52:53], 0
	v_mov_b64_e32 v[54:55], 0
	v_mov_b64_e32 v[72:73], 0
	v_mov_b64_e32 v[74:75], 0
	v_mov_b64_e32 v[64:65], 0
	v_mov_b64_e32 v[66:67], 0
	v_mov_b64_e32 v[88:89], 0
	v_mov_b64_e32 v[90:91], 0
	v_mov_b64_e32 v[80:81], 0
	v_mov_b64_e32 v[82:83], 0
	v_mov_b64_e32 v[104:105], 0
	v_mov_b64_e32 v[106:107], 0
	v_mov_b64_e32 v[96:97], 0
	v_mov_b64_e32 v[98:99], 0
	v_mov_b64_e32 v[120:121], 0
	v_mov_b64_e32 v[122:123], 0
	v_mov_b64_e32 v[112:113], 0
	v_mov_b64_e32 v[114:115], 0
	v_mov_b64_e32 v[76:77], 0
	v_mov_b64_e32 v[78:79], 0
	v_mov_b64_e32 v[68:69], 0
	v_mov_b64_e32 v[70:71], 0
	v_mov_b64_e32 v[92:93], 0
	v_mov_b64_e32 v[94:95], 0
	v_mov_b64_e32 v[84:85], 0
	v_mov_b64_e32 v[86:87], 0
	v_mov_b64_e32 v[108:109], 0
	v_mov_b64_e32 v[110:111], 0
	v_mov_b64_e32 v[100:101], 0
	v_mov_b64_e32 v[102:103], 0
	v_mov_b64_e32 v[124:125], 0
	v_mov_b64_e32 v[126:127], 0
	v_mov_b64_e32 v[116:117], 0
	v_mov_b64_e32 v[118:119], 0

; template <class Epi>
; __device__ __forceinline__ void gemm_phase(LAS unsigned char* lds, const Gemm g, const Sched& S, const Epi& E) {
;     ...
;         const bool has_next = S.next(ui + 1, nxt);
;         const char* nA = has_next ? (const char*)g.A + (size_t)S.aoff(nxt) * 2 : cA; const char* nB = has_next ? (const char*)g.Bt + (size_t)S.boff(nxt) * 2 : cB;
;     ...
;         for (int a = 0; a < 2; ++a)
; #pragma unroll
;             for (int b = 0; b < 2; ++b)
; #pragma unroll
;                 for (int m = 0; m < 4; ++m)
; #pragma unroll
;                     for (int n = 0; n < 2; ++n) acc[a][b][m][n] = (f32x4){0.f, 0.f, 0.f, 0.f};
.LBB0_204:
	s_ashr_i32 s15, s14, 31
	s_lshl_b64 s[22:23], s[14:15], 19
	s_add_u32 s22, s10, s22
	s_addc_u32 s23, s11, s23
	s_and_b64 s[24:25], s[8:9], exec
	s_cselect_b32 s15, s23, s41
	s_cselect_b32 s27, s22, s40
	s_ashr_i32 s21, s20, 31
	s_lshl_b64 s[24:25], s[20:21], 19
	s_add_u32 s24, s53, s24
	s_addc_u32 s25, s54, s25
	s_and_b64 s[46:47], s[8:9], exec
	s_cselect_b32 s21, s25, s45
	s_cselect_b32 s63, s24, s44
	s_add_u32 s40, s40, 0x40080
	s_addc_u32 s41, s41, 0
	s_add_u32 s64, s44, 0x100
	v_mov_b32_e32 v0, 0
	s_addc_u32 s65, s45, 0
	s_mov_b32 s66, -2
	v_mov_b32_e32 v1, 0
	v_mov_b64_e32 v[2:3], 0
	v_mov_b64_e32 v[4:5], 0
	v_mov_b64_e32 v[6:7], 0
	v_mov_b64_e32 v[16:17], 0
	v_mov_b64_e32 v[18:19], 0
	v_mov_b64_e32 v[20:21], 0
	v_mov_b64_e32 v[22:23], 0
	v_mov_b64_e32 v[32:33], 0
	v_mov_b64_e32 v[34:35], 0
	v_mov_b64_e32 v[36:37], 0
	v_mov_b64_e32 v[38:39], 0
	v_mov_b64_e32 v[48:49], 0
	v_mov_b64_e32 v[50:51], 0
	v_mov_b64_e32 v[52:53], 0
	v_mov_b64_e32 v[54:55], 0
	v_mov_b64_e32 v[8:9], 0
	v_mov_b64_e32 v[10:11], 0
	v_mov_b64_e32 v[12:13], 0
	v_mov_b64_e32 v[14:15], 0
	v_mov_b64_e32 v[24:25], 0
	v_mov_b64_e32 v[26:27], 0
	v_mov_b64_e32 v[28:29], 0
	v_mov_b64_e32 v[30:31], 0
	v_mov_b64_e32 v[40:41], 0
	v_mov_b64_e32 v[42:43], 0
	v_mov_b64_e32 v[44:45], 0
	v_mov_b64_e32 v[46:47], 0
	v_mov_b64_e32 v[56:57], 0
	v_mov_b64_e32 v[58:59], 0
	v_mov_b64_e32 v[60:61], 0
	v_mov_b64_e32 v[62:63], 0
	v_mov_b64_e32 v[64:65], 0
	v_mov_b64_e32 v[66:67], 0
	v_mov_b64_e32 v[68:69], 0
	v_mov_b64_e32 v[70:71], 0
	v_mov_b64_e32 v[80:81], 0
	v_mov_b64_e32 v[82:83], 0
	v_mov_b64_e32 v[84:85], 0
	v_mov_b64_e32 v[86:87], 0
	v_mov_b64_e32 v[96:97], 0
	v_mov_b64_e32 v[98:99], 0
	v_mov_b64_e32 v[100:101], 0
	v_mov_b64_e32 v[102:103], 0
	v_mov_b64_e32 v[112:113], 0
	v_mov_b64_e32 v[114:115], 0
	v_mov_b64_e32 v[116:117], 0
	v_mov_b64_e32 v[118:119], 0
	v_mov_b64_e32 v[72:73], 0
	v_mov_b64_e32 v[74:75], 0
	v_mov_b64_e32 v[76:77], 0
	v_mov_b64_e32 v[78:79], 0
	v_mov_b64_e32 v[88:89], 0
	v_mov_b64_e32 v[90:91], 0
	v_mov_b64_e32 v[92:93], 0
	v_mov_b64_e32 v[94:95], 0
	v_mov_b64_e32 v[104:105], 0
	v_mov_b64_e32 v[106:107], 0
	v_mov_b64_e32 v[108:109], 0
	v_mov_b64_e32 v[110:111], 0
	v_mov_b64_e32 v[120:121], 0
	v_mov_b64_e32 v[122:123], 0
	v_mov_b64_e32 v[124:125], 0
	v_mov_b64_e32 v[126:127], 0

; template <class Epi>
; __device__ __forceinline__ void gemm_phase(LAS unsigned char* lds, const Gemm g, const Sched& S, const Epi& E) {
;     ...
;         const bool has_next = S.next(ui + 1, nxt);
;         const char* nA = has_next ? (const char*)g.A + (size_t)S.aoff(nxt) * 2 : cA; const char* nB = has_next ? (const char*)g.Bt + (size_t)S.boff(nxt) * 2 : cB;
;     ...
;         for (int a = 0; a < 2; ++a)
; #pragma unroll
;             for (int b = 0; b < 2; ++b)
; #pragma unroll
;                 for (int m = 0; m < 4; ++m)
; #pragma unroll
;                     for (int n = 0; n < 2; ++n) acc[a][b][m][n] = (f32x4){0.f, 0.f, 0.f, 0.f};
.LBB0_292:
	s_ashr_i32 s23, s22, 31
	s_lshl_b64 s[24:25], s[22:23], 19
	s_add_u32 s24, s46, s24
	s_addc_u32 s25, s47, s25
	s_and_b64 s[26:27], s[8:9], exec
	s_cselect_b32 s23, s25, s29
	s_cselect_b32 s62, s24, s28
	s_ashr_i32 s15, s14, 31
	s_lshl_b64 s[26:27], s[14:15], 19
	s_add_u32 s26, s10, s26
	s_addc_u32 s27, s11, s27
	s_and_b64 s[44:45], s[8:9], exec
	s_cselect_b32 s15, s27, s41
	s_cselect_b32 s63, s26, s40
	s_add_u32 s28, s28, 0x40080
	s_addc_u32 s29, s29, 0
	s_add_u32 s64, s40, 0x100
	v_mov_b32_e32 v0, 0
	s_addc_u32 s65, s41, 0
	s_mov_b32 s66, -2
	v_mov_b32_e32 v1, 0
	v_mov_b64_e32 v[2:3], 0
	v_mov_b64_e32 v[4:5], 0
	v_mov_b64_e32 v[6:7], 0
	v_mov_b64_e32 v[8:9], 0
	v_mov_b64_e32 v[10:11], 0
	v_mov_b64_e32 v[12:13], 0
	v_mov_b64_e32 v[14:15], 0
	v_mov_b64_e32 v[24:25], 0
	v_mov_b64_e32 v[26:27], 0
	v_mov_b64_e32 v[28:29], 0
	v_mov_b64_e32 v[30:31], 0
	v_mov_b64_e32 v[40:41], 0
	v_mov_b64_e32 v[42:43], 0
	v_mov_b64_e32 v[44:45], 0
	v_mov_b64_e32 v[46:47], 0
	v_mov_b64_e32 v[16:17], 0
	v_mov_b64_e32 v[18:19], 0
	v_mov_b64_e32 v[20:21], 0
	v_mov_b64_e32 v[22:23], 0
	v_mov_b64_e32 v[32:33], 0
	v_mov_b64_e32 v[34:35], 0
	v_mov_b64_e32 v[36:37], 0
	v_mov_b64_e32 v[38:39], 0
	v_mov_b64_e32 v[48:49], 0
	v_mov_b64_e32 v[50:51], 0
	v_mov_b64_e32 v[52:53], 0
	v_mov_b64_e32 v[54:55], 0
	v_mov_b64_e32 v[56:57], 0
	v_mov_b64_e32 v[58:59], 0
	v_mov_b64_e32 v[60:61], 0
	v_mov_b64_e32 v[62:63], 0
	v_mov_b64_e32 v[64:65], 0
	v_mov_b64_e32 v[66:67], 0
	v_mov_b64_e32 v[68:69], 0
	v_mov_b64_e32 v[70:71], 0
	v_mov_b64_e32 v[72:73], 0
	v_mov_b64_e32 v[74:75], 0
	v_mov_b64_e32 v[76:77], 0
	v_mov_b64_e32 v[78:79], 0
	v_mov_b64_e32 v[88:89], 0
	v_mov_b64_e32 v[90:91], 0
	v_mov_b64_e32 v[92:93], 0
	v_mov_b64_e32 v[94:95], 0
	v_mov_b64_e32 v[104:105], 0
	v_mov_b64_e32 v[106:107], 0
	v_mov_b64_e32 v[108:109], 0
	v_mov_b64_e32 v[110:111], 0
	v_mov_b64_e32 v[80:81], 0
	v_mov_b64_e32 v[82:83], 0
	v_mov_b64_e32 v[84:85], 0
	v_mov_b64_e32 v[86:87], 0
	v_mov_b64_e32 v[96:97], 0
	v_mov_b64_e32 v[98:99], 0
	v_mov_b64_e32 v[100:101], 0
	v_mov_b64_e32 v[102:103], 0
	v_mov_b64_e32 v[112:113], 0
	v_mov_b64_e32 v[114:115], 0
	v_mov_b64_e32 v[116:117], 0
	v_mov_b64_e32 v[118:119], 0
	v_mov_b64_e32 v[120:121], 0
	v_mov_b64_e32 v[122:123], 0
	v_mov_b64_e32 v[124:125], 0
	v_mov_b64_e32 v[126:127], 0

; template <class Epi>
; __device__ __forceinline__ void gemm_phase(LAS unsigned char* lds, const Gemm g, const Sched& S, const Epi& E) {
;     ...
;     Unit cur, nxt; int ui = 0;
;     if (!S.next(0, cur)) return;
;     f32x4 acc[2][2][4][2];
; #pragma unroll
;     for (int a = 0; a < 2; ++a)
; #pragma unroll
;         for (int b = 0; b < 2; ++b)
; #pragma unroll
;             for (int m = 0; m < 4; ++m)
; #pragma unroll
;                 for (int n = 0; n < 2; ++n) acc[a][b][m][n] = (f32x4){0.f, 0.f, 0.f, 0.f};
;     bf16x8 At[4][2], B0[2][2], B1[2][2];
;     const char* cA = (const char*)g.A + (size_t)S.aoff(cur) * 2; const char* cB = (const char*)g.Bt + (size_t)S.boff(cur) * 2;
.LBB0_380:
	v_mov_b32_e32 v0, 0
	s_mov_b32 s0, s82
	s_mov_b32 s13, s79
	v_mov_b32_e32 v1, 0
	v_mov_b64_e32 v[2:3], 0
	v_mov_b64_e32 v[4:5], 0
	v_mov_b64_e32 v[6:7], 0
	v_mov_b64_e32 v[16:17], 0
	v_mov_b64_e32 v[18:19], 0
	v_mov_b64_e32 v[20:21], 0
	v_mov_b64_e32 v[22:23], 0
	v_mov_b64_e32 v[32:33], 0
	v_mov_b64_e32 v[34:35], 0
	v_mov_b64_e32 v[36:37], 0
	v_mov_b64_e32 v[38:39], 0
	v_mov_b64_e32 v[48:49], 0
	v_mov_b64_e32 v[50:51], 0
	v_mov_b64_e32 v[52:53], 0
	v_mov_b64_e32 v[54:55], 0
	v_mov_b64_e32 v[8:9], 0
	v_mov_b64_e32 v[10:11], 0
	v_mov_b64_e32 v[12:13], 0
	v_mov_b64_e32 v[14:15], 0
	v_mov_b64_e32 v[24:25], 0
	v_mov_b64_e32 v[26:27], 0
	v_mov_b64_e32 v[28:29], 0
	v_mov_b64_e32 v[30:31], 0
	v_mov_b64_e32 v[40:41], 0
	v_mov_b64_e32 v[42:43], 0
	v_mov_b64_e32 v[44:45], 0
	v_mov_b64_e32 v[46:47], 0
	v_mov_b64_e32 v[56:57], 0
	v_mov_b64_e32 v[58:59], 0
	v_mov_b64_e32 v[60:61], 0
	v_mov_b64_e32 v[62:63], 0
	v_mov_b64_e32 v[64:65], 0
	v_mov_b64_e32 v[66:67], 0
	v_mov_b64_e32 v[68:69], 0
	v_mov_b64_e32 v[70:71], 0
	v_mov_b64_e32 v[80:81], 0
	v_mov_b64_e32 v[82:83], 0
	v_mov_b64_e32 v[84:85], 0
	v_mov_b64_e32 v[86:87], 0
	v_mov_b64_e32 v[96:97], 0
	v_mov_b64_e32 v[98:99], 0
	v_mov_b64_e32 v[100:101], 0
	v_mov_b64_e32 v[102:103], 0
	v_mov_b64_e32 v[112:113], 0
	v_mov_b64_e32 v[114:115], 0
	v_mov_b64_e32 v[116:117], 0
	v_mov_b64_e32 v[118:119], 0
	v_mov_b64_e32 v[72:73], 0
	v_mov_b64_e32 v[74:75], 0
	v_mov_b64_e32 v[76:77], 0
	v_mov_b64_e32 v[78:79], 0
	v_mov_b64_e32 v[88:89], 0
	v_mov_b64_e32 v[90:91], 0
	v_mov_b64_e32 v[92:93], 0
	v_mov_b64_e32 v[94:95], 0
	v_mov_b64_e32 v[104:105], 0
	v_mov_b64_e32 v[106:107], 0
	v_mov_b64_e32 v[108:109], 0
	v_mov_b64_e32 v[110:111], 0
	v_mov_b64_e32 v[120:121], 0
	v_mov_b64_e32 v[122:123], 0
	v_mov_b64_e32 v[124:125], 0
	v_mov_b64_e32 v[126:127], 0
	s_andn2_b64 vcc, exec, s[20:21]
	s_cbranch_vccnz .LBB0_382
	s_branch .LBB0_383

; template <class Epi>
; __device__ __forceinline__ void gemm_phase(LAS unsigned char* lds, const Gemm g, const Sched& S, const Epi& E) {
;     ...
;         const bool has_next = S.next(ui + 1, nxt);
;         const char* nA = has_next ? (const char*)g.A + (size_t)S.aoff(nxt) * 2 : cA; const char* nB = has_next ? (const char*)g.Bt + (size_t)S.boff(nxt) * 2 : cB;
;     ...
;         for (int a = 0; a < 2; ++a)
; #pragma unroll
;             for (int b = 0; b < 2; ++b)
; #pragma unroll
;                 for (int m = 0; m < 4; ++m)
; #pragma unroll
;                     for (int n = 0; n < 2; ++n) acc[a][b][m][n] = (f32x4){0.f, 0.f, 0.f, 0.f};
.LBB0_519:
	s_ashr_i32 s27, s26, 31
	s_lshl_b64 s[28:29], s[26:27], 19
	s_add_u32 s28, s82, s28
	s_addc_u32 s29, s83, s29
	s_and_b64 s[40:41], s[22:23], exec
	s_cselect_b32 s0, s29, s3
	s_cselect_b32 s27, s28, s2
	s_ashr_i32 s25, s24, 31
	s_lshl_b64 s[40:41], s[24:25], 19
	s_add_u32 s40, s78, s40
	s_addc_u32 s41, s79, s41
	s_and_b64 s[52:53], s[22:23], exec
	s_cselect_b32 s25, s41, s5
	s_cselect_b32 s54, s40, s4
	s_add_u32 s2, s2, 0x40080
	s_addc_u32 s3, s3, 0
	s_add_u32 s55, s4, 0x100
	v_mov_b32_e32 v0, 0
	s_addc_u32 s56, s5, 0
	s_mov_b32 s57, -2
	v_mov_b32_e32 v1, 0
	v_mov_b64_e32 v[2:3], 0
	v_mov_b64_e32 v[8:9], 0
	v_mov_b64_e32 v[10:11], 0
	v_mov_b64_e32 v[16:17], 0
	v_mov_b64_e32 v[18:19], 0
	v_mov_b64_e32 v[24:25], 0
	v_mov_b64_e32 v[26:27], 0
	v_mov_b64_e32 v[32:33], 0
	v_mov_b64_e32 v[34:35], 0
	v_mov_b64_e32 v[40:41], 0
	v_mov_b64_e32 v[42:43], 0
	v_mov_b64_e32 v[48:49], 0
	v_mov_b64_e32 v[50:51], 0
	v_mov_b64_e32 v[56:57], 0
	v_mov_b64_e32 v[58:59], 0
	v_mov_b64_e32 v[4:5], 0
	v_mov_b64_e32 v[6:7], 0
	v_mov_b64_e32 v[12:13], 0
	v_mov_b64_e32 v[14:15], 0
	v_mov_b64_e32 v[20:21], 0
	v_mov_b64_e32 v[22:23], 0
	v_mov_b64_e32 v[28:29], 0
	v_mov_b64_e32 v[30:31], 0
	v_mov_b64_e32 v[36:37], 0
	v_mov_b64_e32 v[38:39], 0
	v_mov_b64_e32 v[44:45], 0
	v_mov_b64_e32 v[46:47], 0
	v_mov_b64_e32 v[52:53], 0
	v_mov_b64_e32 v[54:55], 0
	v_mov_b64_e32 v[60:61], 0
	v_mov_b64_e32 v[62:63], 0
	v_mov_b64_e32 v[64:65], 0
	v_mov_b64_e32 v[66:67], 0
	v_mov_b64_e32 v[72:73], 0
	v_mov_b64_e32 v[74:75], 0
	v_mov_b64_e32 v[80:81], 0
	v_mov_b64_e32 v[82:83], 0
	v_mov_b64_e32 v[88:89], 0
	v_mov_b64_e32 v[90:91], 0
	v_mov_b64_e32 v[96:97], 0
	v_mov_b64_e32 v[98:99], 0
	v_mov_b64_e32 v[104:105], 0
	v_mov_b64_e32 v[106:107], 0
	v_mov_b64_e32 v[112:113], 0
	v_mov_b64_e32 v[114:115], 0
	v_mov_b64_e32 v[120:121], 0
	v_mov_b64_e32 v[122:123], 0
	v_mov_b64_e32 v[68:69], 0
	v_mov_b64_e32 v[70:71], 0
	v_mov_b64_e32 v[76:77], 0
	v_mov_b64_e32 v[78:79], 0
	v_mov_b64_e32 v[84:85], 0
	v_mov_b64_e32 v[86:87], 0
	v_mov_b64_e32 v[92:93], 0
	v_mov_b64_e32 v[94:95], 0
	v_mov_b64_e32 v[100:101], 0
	v_mov_b64_e32 v[102:103], 0
	v_mov_b64_e32 v[108:109], 0
	v_mov_b64_e32 v[110:111], 0
	v_mov_b64_e32 v[116:117], 0
	v_mov_b64_e32 v[118:119], 0
	v_mov_b64_e32 v[124:125], 0
	v_mov_b64_e32 v[126:127], 0

; template <class Epi>
; __device__ __forceinline__ void gemm_phase(LAS unsigned char* lds, const Gemm g, const Sched& S, const Epi& E) {
;     ...
;         const bool has_next = S.next(ui + 1, nxt);
;         const char* nA = has_next ? (const char*)g.A + (size_t)S.aoff(nxt) * 2 : cA; const char* nB = has_next ? (const char*)g.Bt + (size_t)S.boff(nxt) * 2 : cB;
;     ...
;         for (int a = 0; a < 2; ++a)
; #pragma unroll
;             for (int b = 0; b < 2; ++b)
; #pragma unroll
;                 for (int m = 0; m < 4; ++m)
; #pragma unroll
;                     for (int n = 0; n < 2; ++n) acc[a][b][m][n] = (f32x4){0.f, 0.f, 0.f, 0.f};
.LBB0_772:
	s_ashr_i32 s25, s24, 31
	s_lshl_b64 s[40:41], s[24:25], 17
	s_add_u32 s40, s68, s40
	s_addc_u32 s41, s69, s41
	s_cmp_gt_i32 s26, 7
	s_cselect_b32 s98, 0x100, 0
	s_add_u32 s40, s40, s98
	s_addc_u32 s41, s41, 0
	s_and_b64 s[44:45], s[28:29], exec
	s_cselect_b32 s3, s41, s47
	s_cselect_b32 s5, s40, s46
	s_ashr_i32 s27, s26, 31
	s_lshl_b64 s[44:45], s[26:27], 17
	s_add_u32 s44, s30, s44
	s_addc_u32 s45, s31, s45
	s_add_u32 s44, s44, s98
	s_addc_u32 s45, s45, 0
	s_and_b64 s[54:55], s[28:29], exec
	v_mov_b32_e32 v0, 0
	s_cselect_b32 s25, s45, s53
	s_cselect_b32 s27, s44, s52
	s_mov_b64 s[74:75], 0
	s_mov_b64 s[54:55], 0
	s_mov_b64 s[56:57], -1
	v_mov_b32_e32 v1, 0
	v_mov_b64_e32 v[2:3], 0
	v_mov_b64_e32 v[4:5], 0
	v_mov_b64_e32 v[6:7], 0
	v_mov_b64_e32 v[8:9], 0
	v_mov_b64_e32 v[10:11], 0
	v_mov_b64_e32 v[12:13], 0
	v_mov_b64_e32 v[14:15], 0
	v_mov_b64_e32 v[16:17], 0
	v_mov_b64_e32 v[18:19], 0
	v_mov_b64_e32 v[20:21], 0
	v_mov_b64_e32 v[22:23], 0
	v_mov_b64_e32 v[24:25], 0
	v_mov_b64_e32 v[26:27], 0
	v_mov_b64_e32 v[28:29], 0
	v_mov_b64_e32 v[30:31], 0
	v_mov_b64_e32 v[64:65], 0
	v_mov_b64_e32 v[66:67], 0
	v_mov_b64_e32 v[68:69], 0
	v_mov_b64_e32 v[70:71], 0
	v_mov_b64_e32 v[72:73], 0
	v_mov_b64_e32 v[74:75], 0
	v_mov_b64_e32 v[76:77], 0
	v_mov_b64_e32 v[78:79], 0
	v_mov_b64_e32 v[88:89], 0
	v_mov_b64_e32 v[90:91], 0
	v_mov_b64_e32 v[92:93], 0
	v_mov_b64_e32 v[94:95], 0
	v_mov_b64_e32 v[96:97], 0
	v_mov_b64_e32 v[98:99], 0
	v_mov_b64_e32 v[100:101], 0
	v_mov_b64_e32 v[102:103], 0
	v_mov_b64_e32 v[32:33], 0
	v_mov_b64_e32 v[34:35], 0
	v_mov_b64_e32 v[36:37], 0
	v_mov_b64_e32 v[38:39], 0
	v_mov_b64_e32 v[40:41], 0
	v_mov_b64_e32 v[42:43], 0
	v_mov_b64_e32 v[44:45], 0
	v_mov_b64_e32 v[46:47], 0
	v_mov_b64_e32 v[48:49], 0
	v_mov_b64_e32 v[50:51], 0
	v_mov_b64_e32 v[52:53], 0
	v_mov_b64_e32 v[54:55], 0
	v_mov_b64_e32 v[56:57], 0
	v_mov_b64_e32 v[58:59], 0
	v_mov_b64_e32 v[60:61], 0
	v_mov_b64_e32 v[62:63], 0
	v_mov_b64_e32 v[104:105], 0
	v_mov_b64_e32 v[106:107], 0
	v_mov_b64_e32 v[108:109], 0
	v_mov_b64_e32 v[110:111], 0
	v_mov_b64_e32 v[112:113], 0
	v_mov_b64_e32 v[114:115], 0
	v_mov_b64_e32 v[116:117], 0
	v_mov_b64_e32 v[118:119], 0
	v_mov_b64_e32 v[120:121], 0
	v_mov_b64_e32 v[122:123], 0
	v_mov_b64_e32 v[124:125], 0
	v_mov_b64_e32 v[126:127], 0
	v_mov_b64_e32 v[128:129], 0
	v_mov_b64_e32 v[130:131], 0
	v_mov_b64_e32 v[132:133], 0
	v_mov_b64_e32 v[134:135], 0

; template <class Epi>
; __device__ __forceinline__ void gemm_phase(LAS unsigned char* lds, const Gemm g, const Sched& S, const Epi& E) {
;     ...
;         const bool has_next = S.next(ui + 1, nxt);
;         const char* nA = has_next ? (const char*)g.A + (size_t)S.aoff(nxt) * 2 : cA; const char* nB = has_next ? (const char*)g.Bt + (size_t)S.boff(nxt) * 2 : cB;
;     ...
;         for (int a = 0; a < 2; ++a)
; #pragma unroll
;             for (int b = 0; b < 2; ++b)
; #pragma unroll
;                 for (int m = 0; m < 4; ++m)
; #pragma unroll
;                     for (int n = 0; n < 2; ++n) acc[a][b][m][n] = (f32x4){0.f, 0.f, 0.f, 0.f};
.LBB0_899:
	s_ashr_i32 s57, s56, 31
	s_lshl_b64 s[14:15], s[56:57], 17
	s_add_u32 s76, s40, s14
	s_addc_u32 s77, s41, s15
	s_bitcmp1_b32 s56, 0
	s_cselect_b32 s98, 0x100, 0
	s_add_u32 s76, s76, s98
	s_addc_u32 s77, s77, 0
	s_and_b64 s[8:9], s[8:9], exec
	v_mov_b32_e32 v0, 0
	s_cselect_b32 s1, s77, s7
	s_cselect_b32 s55, s76, s6
	s_mov_b64 s[78:79], 0
	s_mov_b64 s[8:9], 0
	s_mov_b64 s[14:15], -1
	v_mov_b32_e32 v1, 0
	v_mov_b64_e32 v[2:3], 0
	v_mov_b64_e32 v[4:5], 0
	v_mov_b64_e32 v[6:7], 0
	v_mov_b64_e32 v[8:9], 0
	v_mov_b64_e32 v[10:11], 0
	v_mov_b64_e32 v[12:13], 0
	v_mov_b64_e32 v[14:15], 0
	v_mov_b64_e32 v[16:17], 0
	v_mov_b64_e32 v[18:19], 0
	v_mov_b64_e32 v[20:21], 0
	v_mov_b64_e32 v[22:23], 0
	v_mov_b64_e32 v[24:25], 0
	v_mov_b64_e32 v[26:27], 0
	v_mov_b64_e32 v[28:29], 0
	v_mov_b64_e32 v[30:31], 0
	v_mov_b64_e32 v[64:65], 0
	v_mov_b64_e32 v[66:67], 0
	v_mov_b64_e32 v[68:69], 0
	v_mov_b64_e32 v[70:71], 0
	v_mov_b64_e32 v[72:73], 0
	v_mov_b64_e32 v[74:75], 0
	v_mov_b64_e32 v[76:77], 0
	v_mov_b64_e32 v[78:79], 0
	v_mov_b64_e32 v[80:81], 0
	v_mov_b64_e32 v[82:83], 0
	v_mov_b64_e32 v[84:85], 0
	v_mov_b64_e32 v[86:87], 0
	v_mov_b64_e32 v[88:89], 0
	v_mov_b64_e32 v[90:91], 0
	v_mov_b64_e32 v[92:93], 0
	v_mov_b64_e32 v[94:95], 0
	v_mov_b64_e32 v[32:33], 0
	v_mov_b64_e32 v[34:35], 0
	v_mov_b64_e32 v[36:37], 0
	v_mov_b64_e32 v[38:39], 0
	v_mov_b64_e32 v[40:41], 0
	v_mov_b64_e32 v[42:43], 0
	v_mov_b64_e32 v[44:45], 0
	v_mov_b64_e32 v[46:47], 0
	v_mov_b64_e32 v[48:49], 0
	v_mov_b64_e32 v[50:51], 0
	v_mov_b64_e32 v[52:53], 0
	v_mov_b64_e32 v[54:55], 0
	v_mov_b64_e32 v[56:57], 0
	v_mov_b64_e32 v[58:59], 0
	v_mov_b64_e32 v[60:61], 0
	v_mov_b64_e32 v[62:63], 0
	v_mov_b64_e32 v[104:105], 0
	v_mov_b64_e32 v[106:107], 0
	v_mov_b64_e32 v[108:109], 0
	v_mov_b64_e32 v[110:111], 0
	v_mov_b64_e32 v[112:113], 0
	v_mov_b64_e32 v[114:115], 0
	v_mov_b64_e32 v[116:117], 0
	v_mov_b64_e32 v[118:119], 0
	v_mov_b64_e32 v[120:121], 0
	v_mov_b64_e32 v[122:123], 0
	v_mov_b64_e32 v[124:125], 0
	v_mov_b64_e32 v[126:127], 0
	v_mov_b64_e32 v[128:129], 0
	v_mov_b64_e32 v[130:131], 0
	v_mov_b64_e32 v[132:133], 0
	v_mov_b64_e32 v[134:135], 0

; template <class Epi>
; __device__ __forceinline__ void gemm_phase(LAS unsigned char* lds, const Gemm g, const Sched& S, const Epi& E) {
;     ...
;     Unit cur, nxt; int ui = 0;
;     if (!S.next(0, cur)) return;
;     f32x4 acc[2][2][4][2];
; #pragma unroll
;     for (int a = 0; a < 2; ++a)
; #pragma unroll
;         for (int b = 0; b < 2; ++b)
; #pragma unroll
;             for (int m = 0; m < 4; ++m)
; #pragma unroll
;                 for (int n = 0; n < 2; ++n) acc[a][b][m][n] = (f32x4){0.f, 0.f, 0.f, 0.f};
;     bf16x8 At[4][2], B0[2][2], B1[2][2];
;     const char* cA = (const char*)g.A + (size_t)S.aoff(cur) * 2; const char* cB = (const char*)g.Bt + (size_t)S.boff(cur) * 2;
.LBB0_1220:
	v_mov_b32_e32 v0, 0
	s_mov_b32 s0, s26
	s_mov_b32 s20, s24
	v_mov_b32_e32 v1, 0
	v_mov_b64_e32 v[2:3], 0
	v_mov_b64_e32 v[4:5], 0
	v_mov_b64_e32 v[6:7], 0
	v_mov_b64_e32 v[16:17], 0
	v_mov_b64_e32 v[18:19], 0
	v_mov_b64_e32 v[20:21], 0
	v_mov_b64_e32 v[22:23], 0
	v_mov_b64_e32 v[32:33], 0
	v_mov_b64_e32 v[34:35], 0
	v_mov_b64_e32 v[36:37], 0
	v_mov_b64_e32 v[38:39], 0
	v_mov_b64_e32 v[48:49], 0
	v_mov_b64_e32 v[50:51], 0
	v_mov_b64_e32 v[52:53], 0
	v_mov_b64_e32 v[54:55], 0
	v_mov_b64_e32 v[8:9], 0
	v_mov_b64_e32 v[10:11], 0
	v_mov_b64_e32 v[12:13], 0
	v_mov_b64_e32 v[14:15], 0
	v_mov_b64_e32 v[24:25], 0
	v_mov_b64_e32 v[26:27], 0
	v_mov_b64_e32 v[28:29], 0
	v_mov_b64_e32 v[30:31], 0
	v_mov_b64_e32 v[40:41], 0
	v_mov_b64_e32 v[42:43], 0
	v_mov_b64_e32 v[44:45], 0
	v_mov_b64_e32 v[46:47], 0
	v_mov_b64_e32 v[56:57], 0
	v_mov_b64_e32 v[58:59], 0
	v_mov_b64_e32 v[60:61], 0
	v_mov_b64_e32 v[62:63], 0
	v_mov_b64_e32 v[64:65], 0
	v_mov_b64_e32 v[66:67], 0
	v_mov_b64_e32 v[68:69], 0
	v_mov_b64_e32 v[70:71], 0
	v_mov_b64_e32 v[80:81], 0
	v_mov_b64_e32 v[82:83], 0
	v_mov_b64_e32 v[84:85], 0
	v_mov_b64_e32 v[86:87], 0
	v_mov_b64_e32 v[96:97], 0
	v_mov_b64_e32 v[98:99], 0
	v_mov_b64_e32 v[100:101], 0
	v_mov_b64_e32 v[102:103], 0
	v_mov_b64_e32 v[112:113], 0
	v_mov_b64_e32 v[114:115], 0
	v_mov_b64_e32 v[116:117], 0
	v_mov_b64_e32 v[118:119], 0
	v_mov_b64_e32 v[72:73], 0
	v_mov_b64_e32 v[74:75], 0
	v_mov_b64_e32 v[76:77], 0
	v_mov_b64_e32 v[78:79], 0
	v_mov_b64_e32 v[88:89], 0
	v_mov_b64_e32 v[90:91], 0
	v_mov_b64_e32 v[92:93], 0
	v_mov_b64_e32 v[94:95], 0
	v_mov_b64_e32 v[104:105], 0
	v_mov_b64_e32 v[106:107], 0
	v_mov_b64_e32 v[108:109], 0
	v_mov_b64_e32 v[110:111], 0
	v_mov_b64_e32 v[120:121], 0
	v_mov_b64_e32 v[122:123], 0
	v_mov_b64_e32 v[124:125], 0
	v_mov_b64_e32 v[126:127], 0
	s_andn2_b64 vcc, exec, s[28:29]
	s_cbranch_vccnz .LBB0_1222
	s_branch .LBB0_1223

; template <class Epi>
; __device__ __forceinline__ void gemm_phase(LAS unsigned char* lds, const Gemm g, const Sched& S, const Epi& E) {
;     ...
;         const bool has_next = S.next(ui + 1, nxt);
;         const char* nA = has_next ? (const char*)g.A + (size_t)S.aoff(nxt) * 2 : cA; const char* nB = has_next ? (const char*)g.Bt + (size_t)S.boff(nxt) * 2 : cB;
;     ...
;         for (int a = 0; a < 2; ++a)
; #pragma unroll
;             for (int b = 0; b < 2; ++b)
; #pragma unroll
;                 for (int m = 0; m < 4; ++m)
; #pragma unroll
;                     for (int n = 0; n < 2; ++n) acc[a][b][m][n] = (f32x4){0.f, 0.f, 0.f, 0.f};
.LBB0_1354:
	s_ashr_i32 s23, s22, 31
	s_lshl_b64 s[26:27], s[22:23], 19
	s_add_u32 s26, s8, s26
	s_addc_u32 s27, s9, s27
	s_and_b64 s[28:29], s[20:21], exec
	s_cselect_b32 s23, s27, s39
	s_cselect_b32 s50, s26, s38
	s_ashr_i32 s25, s24, 31
	s_lshl_b64 s[28:29], s[24:25], 19
	s_add_u32 s28, s6, s28
	s_addc_u32 s29, s7, s29
	s_and_b64 s[42:43], s[20:21], exec
	s_cselect_b32 s25, s29, s41
	s_cselect_b32 s51, s28, s40
	s_add_u32 s38, s38, 0x40080
	s_addc_u32 s39, s39, 0
	s_add_u32 s52, s40, 0x100
	v_mov_b32_e32 v0, 0
	s_addc_u32 s53, s41, 0
	s_mov_b32 s54, -2
	v_mov_b32_e32 v1, 0
	v_mov_b64_e32 v[2:3], 0
	v_mov_b64_e32 v[4:5], 0
	v_mov_b64_e32 v[6:7], 0
	v_mov_b64_e32 v[8:9], 0
	v_mov_b64_e32 v[10:11], 0
	v_mov_b64_e32 v[16:17], 0
	v_mov_b64_e32 v[18:19], 0
	v_mov_b64_e32 v[24:25], 0
	v_mov_b64_e32 v[26:27], 0
	v_mov_b64_e32 v[32:33], 0
	v_mov_b64_e32 v[34:35], 0
	v_mov_b64_e32 v[40:41], 0
	v_mov_b64_e32 v[42:43], 0
	v_mov_b64_e32 v[48:49], 0
	v_mov_b64_e32 v[50:51], 0
	v_mov_b64_e32 v[12:13], 0
	v_mov_b64_e32 v[14:15], 0
	v_mov_b64_e32 v[20:21], 0
	v_mov_b64_e32 v[22:23], 0
	v_mov_b64_e32 v[28:29], 0
	v_mov_b64_e32 v[30:31], 0
	v_mov_b64_e32 v[36:37], 0
	v_mov_b64_e32 v[38:39], 0
	v_mov_b64_e32 v[44:45], 0
	v_mov_b64_e32 v[46:47], 0
	v_mov_b64_e32 v[52:53], 0
	v_mov_b64_e32 v[54:55], 0
	v_mov_b64_e32 v[56:57], 0
	v_mov_b64_e32 v[58:59], 0
	v_mov_b64_e32 v[60:61], 0
	v_mov_b64_e32 v[62:63], 0
	v_mov_b64_e32 v[64:65], 0
	v_mov_b64_e32 v[66:67], 0
	v_mov_b64_e32 v[68:69], 0
	v_mov_b64_e32 v[70:71], 0
	v_mov_b64_e32 v[72:73], 0
	v_mov_b64_e32 v[74:75], 0
	v_mov_b64_e32 v[80:81], 0
	v_mov_b64_e32 v[82:83], 0
	v_mov_b64_e32 v[88:89], 0
	v_mov_b64_e32 v[90:91], 0
	v_mov_b64_e32 v[96:97], 0
	v_mov_b64_e32 v[98:99], 0
	v_mov_b64_e32 v[104:105], 0
	v_mov_b64_e32 v[106:107], 0
	v_mov_b64_e32 v[112:113], 0
	v_mov_b64_e32 v[114:115], 0
	v_mov_b64_e32 v[76:77], 0
	v_mov_b64_e32 v[78:79], 0
	v_mov_b64_e32 v[84:85], 0
	v_mov_b64_e32 v[86:87], 0
	v_mov_b64_e32 v[92:93], 0
	v_mov_b64_e32 v[94:95], 0
	v_mov_b64_e32 v[100:101], 0
	v_mov_b64_e32 v[102:103], 0
	v_mov_b64_e32 v[108:109], 0
	v_mov_b64_e32 v[110:111], 0
	v_mov_b64_e32 v[116:117], 0
	v_mov_b64_e32 v[118:119], 0
	v_mov_b64_e32 v[120:121], 0
	v_mov_b64_e32 v[122:123], 0
	v_mov_b64_e32 v[124:125], 0
	v_mov_b64_e32 v[126:127], 0

; #define PG8_STAGE(bufoff, gbase, voff) do { _Pragma("unroll") for (int _i = 0; _i < 2; ++_i) \
;         __builtin_amdgcn_global_load_lds((const unsigned*)((const char*)(gbase) + (voff)[_i]), (LAS unsigned*)(lds + (bufoff) + ldsw + _i * 8192), 16, 0, 0); } while (0)
; #define PG8_WAIT_V(n) asm volatile("s_waitcnt vmcnt(" #n ")" ::: "memory")
; #define PG8_BAR __builtin_amdgcn_s_barrier()
; template <class Epi>
; __device__ __forceinline__ void gemm_phase(LAS unsigned char* lds, const Gemm g, const Sched& S, const Epi& E) {
;     ...
;     f32x4 acc[2][2][4][2];
; #pragma unroll
;     for (int a = 0; a < 2; ++a)
; #pragma unroll
;         for (int b = 0; b < 2; ++b)
; #pragma unroll
;             for (int m = 0; m < 4; ++m)
; #pragma unroll
;                 for (int n = 0; n < 2; ++n) acc[a][b][m][n] = (f32x4){0.f, 0.f, 0.f, 0.f};
;     bf16x8 At[4][2], B0[2][2], B1[2][2];
;     const char* cA = (const char*)g.A + (size_t)S.aoff(cur) * 2; const char* cB = (const char*)g.Bt + (size_t)S.boff(cur) * 2;
;     PG8_STAGE(PG8_SB(0, 0), cB, voffB); PG8_STAGE(PG8_SB(0, 1), cB + hstepB, voffB); PG8_STAGE(PG8_SA(0, 0), cA, voffA); PG8_STAGE(PG8_SA(0, 1), cA + hstepA, voffA);
;     if (wr == 1) PG8_BAR;
;     PG8_WAIT_V(2); PG8_BAR;
;     PG8_STAGE(PG8_SB(1, 0), cB + kstep, voffB); PG8_STAGE(PG8_SA(1, 0), cA + kstep, voffA); PG8_STAGE(PG8_SB(1, 1), cB + hstepB + kstep, voffB);
;     PG8_WAIT_V(6); PG8_BAR;
.LBB0_1369:
	v_and_b32_e32 v139, 15, v8
	v_bfe_u32 v137, v8, 4, 2
	v_lshlrev_b32_e32 v8, 4, v137
	v_lshlrev_b32_e32 v138, 2, v139
	s_mov_b64 s[24:25], 0x80
	s_and_b32 s11, s4, 3
	v_lshl_or_b32 v8, v139, 6, v8
	s_lshl_b32 s4, s56, 13
	v_and_b32_e32 v9, 32, v138
	s_add_i32 m0, s17, 0x18000
	v_lshl_add_u64 v[6:7], v[6:7], 0, s[24:25]
	v_bitop3_b32 v10, v8, s4, v9 bitop3:0xde
	s_lshl_b32 s4, s11, 12
	s_waitcnt vmcnt(2)
	s_barrier
	global_load_lds_dwordx4 v[6:7], off
	v_lshl_add_u64 v[4:5], v[4:5], 0, s[24:25]
	s_add_i32 m0, s17, 0x1a000
	s_add_i32 s64, s17, 0x8000
	s_add_i32 s65, s17, 0xa000
	v_bitop3_b32 v140, v8, s4, v9 bitop3:0xde
	global_load_lds_dwordx4 v[4:5], off
	v_lshl_add_u64 v[0:1], v[0:1], 0, s[24:25]
	s_mov_b32 m0, s64
	s_add_u32 s4, s20, 0x40080
	global_load_lds_dwordx4 v[0:1], off
	v_lshl_add_u64 v[0:1], v[2:3], 0, s[24:25]
	s_mov_b32 m0, s65
	s_addc_u32 s5, s21, 0
	global_load_lds_dwordx4 v[0:1], off
	s_add_i32 m0, s17, 0x1c000
	v_lshl_add_u64 v[0:1], s[4:5], 0, v[130:131]
	global_load_lds_dwordx4 v[0:1], off
	v_lshl_add_u64 v[0:1], s[4:5], 0, v[134:135]
	s_add_i32 m0, s17, 0x1e000
	s_cmpk_lt_u32 s13, 0x100
	global_load_lds_dwordx4 v[0:1], off
	s_waitcnt vmcnt(6)
	v_lshl_or_b32 v136, s56, 6, v139
	s_cselect_b64 s[26:27], -1, 0
	s_add_i32 s66, 0, 0x10000
	s_add_i32 s67, 0, 0x14000
	v_add_u32_e32 v141, 0, v10
	v_mov_b64_e32 v[0:1], 0
	v_mov_b64_e32 v[2:3], 0
	v_mov_b64_e32 v[4:5], 0
	v_mov_b64_e32 v[6:7], 0
	v_mov_b64_e32 v[8:9], 0
	v_mov_b64_e32 v[10:11], 0
	v_mov_b64_e32 v[16:17], 0
	v_mov_b64_e32 v[18:19], 0
	v_mov_b64_e32 v[24:25], 0
	v_mov_b64_e32 v[26:27], 0
	v_mov_b64_e32 v[32:33], 0
	v_mov_b64_e32 v[34:35], 0
	v_mov_b64_e32 v[40:41], 0
	v_mov_b64_e32 v[42:43], 0
	v_mov_b64_e32 v[48:49], 0
	v_mov_b64_e32 v[50:51], 0
	v_mov_b64_e32 v[12:13], 0
	v_mov_b64_e32 v[14:15], 0
	v_mov_b64_e32 v[20:21], 0
	v_mov_b64_e32 v[22:23], 0
	v_mov_b64_e32 v[28:29], 0
	v_mov_b64_e32 v[30:31], 0
	v_mov_b64_e32 v[36:37], 0
	v_mov_b64_e32 v[38:39], 0
	v_mov_b64_e32 v[44:45], 0
	v_mov_b64_e32 v[46:47], 0
	v_mov_b64_e32 v[52:53], 0
	v_mov_b64_e32 v[54:55], 0
	v_mov_b64_e32 v[56:57], 0
	v_mov_b64_e32 v[58:59], 0
	v_mov_b64_e32 v[60:61], 0
	v_mov_b64_e32 v[62:63], 0
	v_mov_b64_e32 v[64:65], 0
	v_mov_b64_e32 v[66:67], 0
	v_mov_b64_e32 v[68:69], 0
	v_mov_b64_e32 v[70:71], 0
	v_mov_b64_e32 v[72:73], 0
	v_mov_b64_e32 v[74:75], 0
	v_mov_b64_e32 v[80:81], 0
	v_mov_b64_e32 v[82:83], 0
	v_mov_b64_e32 v[88:89], 0
	v_mov_b64_e32 v[90:91], 0
	v_mov_b64_e32 v[96:97], 0
	v_mov_b64_e32 v[98:99], 0
	v_mov_b64_e32 v[104:105], 0
	v_mov_b64_e32 v[106:107], 0
	v_mov_b64_e32 v[116:117], 0
	v_mov_b64_e32 v[118:119], 0
	v_mov_b64_e32 v[76:77], 0
	v_mov_b64_e32 v[78:79], 0
	v_mov_b64_e32 v[84:85], 0
	v_mov_b64_e32 v[86:87], 0
	v_mov_b64_e32 v[92:93], 0
	v_mov_b64_e32 v[94:95], 0
	v_mov_b64_e32 v[100:101], 0
	v_mov_b64_e32 v[102:103], 0
	v_mov_b64_e32 v[108:109], 0
	v_mov_b64_e32 v[110:111], 0
	v_mov_b64_e32 v[112:113], 0
	v_mov_b64_e32 v[114:115], 0
	v_mov_b64_e32 v[120:121], 0
	v_mov_b64_e32 v[122:123], 0
	v_mov_b64_e32 v[124:125], 0
	v_mov_b64_e32 v[126:127], 0
	s_barrier
	s_branch .LBB0_1372
.LBB0_1370:
	v_mov_b32_e32 v0, 0
	s_mov_b32 s10, s68
	s_mov_b32 s16, s28
	s_mov_b64 s[20:21], s[38:39]
	s_mov_b64 s[18:19], s[40:41]
	s_mov_b32 s63, s69
	v_mov_b32_e32 v1, 0
	v_mov_b64_e32 v[2:3], 0
	v_mov_b64_e32 v[4:5], 0
	v_mov_b64_e32 v[6:7], 0
	v_mov_b64_e32 v[8:9], 0
	v_mov_b64_e32 v[10:11], 0
	v_mov_b64_e32 v[16:17], 0
	v_mov_b64_e32 v[18:19], 0
	v_mov_b64_e32 v[24:25], 0
	v_mov_b64_e32 v[26:27], 0
	v_mov_b64_e32 v[32:33], 0
	v_mov_b64_e32 v[34:35], 0
	v_mov_b64_e32 v[40:41], 0
	v_mov_b64_e32 v[42:43], 0
	v_mov_b64_e32 v[48:49], 0
	v_mov_b64_e32 v[50:51], 0
	v_mov_b64_e32 v[12:13], 0
	v_mov_b64_e32 v[14:15], 0
	v_mov_b64_e32 v[20:21], 0
	v_mov_b64_e32 v[22:23], 0
	v_mov_b64_e32 v[28:29], 0
	v_mov_b64_e32 v[30:31], 0
	v_mov_b64_e32 v[36:37], 0
	v_mov_b64_e32 v[38:39], 0
	v_mov_b64_e32 v[44:45], 0
	v_mov_b64_e32 v[46:47], 0
	v_mov_b64_e32 v[52:53], 0
	v_mov_b64_e32 v[54:55], 0
	v_mov_b64_e32 v[56:57], 0
	v_mov_b64_e32 v[58:59], 0
	v_mov_b64_e32 v[60:61], 0
	v_mov_b64_e32 v[62:63], 0
	v_mov_b64_e32 v[64:65], 0
	v_mov_b64_e32 v[66:67], 0
	v_mov_b64_e32 v[68:69], 0
	v_mov_b64_e32 v[70:71], 0
	v_mov_b64_e32 v[72:73], 0
	v_mov_b64_e32 v[74:75], 0
	v_mov_b64_e32 v[80:81], 0
	v_mov_b64_e32 v[82:83], 0
	v_mov_b64_e32 v[88:89], 0
	v_mov_b64_e32 v[90:91], 0
	v_mov_b64_e32 v[96:97], 0
	v_mov_b64_e32 v[98:99], 0
	v_mov_b64_e32 v[104:105], 0
	v_mov_b64_e32 v[106:107], 0
	v_mov_b64_e32 v[116:117], 0
	v_mov_b64_e32 v[118:119], 0
	v_mov_b64_e32 v[76:77], 0
	v_mov_b64_e32 v[78:79], 0
	v_mov_b64_e32 v[84:85], 0
	v_mov_b64_e32 v[86:87], 0
	v_mov_b64_e32 v[92:93], 0
	v_mov_b64_e32 v[94:95], 0
	v_mov_b64_e32 v[100:101], 0
	v_mov_b64_e32 v[102:103], 0
	v_mov_b64_e32 v[108:109], 0
	v_mov_b64_e32 v[110:111], 0
	v_mov_b64_e32 v[112:113], 0
	v_mov_b64_e32 v[114:115], 0
	v_mov_b64_e32 v[120:121], 0
	v_mov_b64_e32 v[122:123], 0
	v_mov_b64_e32 v[124:125], 0
	v_mov_b64_e32 v[126:127], 0

;     __device__ __forceinline__ long aoff(const Unit& u) const {
;         long o = (long)u.pm * 256 * lda;
;         if (mode == 1) o += 256 * (u.pn >> 1); else if (mode >= 2) o += u.pn * 256;
;         return o;
;     }
; template <class Epi>
; __device__ __forceinline__ void gemm_phase(LAS unsigned char* lds, const Gemm g, const Sched& S, const Epi& E) {
;     ...
;         for (int a = 0; a < 2; ++a)
; #pragma unroll
;             for (int b = 0; b < 2; ++b)
; #pragma unroll
;                 for (int m = 0; m < 4; ++m)
; #pragma unroll
;                     for (int n = 0; n < 2; ++n) acc[a][b][m][n] = (f32x4){0.f, 0.f, 0.f, 0.f};
.LBB0_1438:
	s_lshl_b32 s40, s22, 8
	s_ashr_i32 s25, s24, 31
	s_ashr_i32 s41, s40, 31
	s_lshl_b64 s[44:45], s[24:25], 19
	s_lshl_b64 s[40:41], s[40:41], 1
	s_add_u32 s23, s14, s44
	s_addc_u32 s25, s15, s45
	s_add_u32 s40, s23, s40
	s_addc_u32 s41, s25, s41
	s_and_b64 s[42:43], s[42:43], exec
	v_mov_b32_e32 v0, 0
	s_cselect_b32 s23, s41, s29
	s_cselect_b32 s25, s40, s28
	s_mov_b32 s46, 0
	s_mov_b64 s[42:43], -1
	s_mov_b64 s[44:45], 0
	v_mov_b32_e32 v1, 0
	v_mov_b64_e32 v[2:3], 0
	v_mov_b64_e32 v[4:5], 0
	v_mov_b64_e32 v[6:7], 0
	v_mov_b64_e32 v[8:9], 0
	v_mov_b64_e32 v[10:11], 0
	v_mov_b64_e32 v[12:13], 0
	v_mov_b64_e32 v[14:15], 0
	v_mov_b64_e32 v[24:25], 0
	v_mov_b64_e32 v[26:27], 0
	v_mov_b64_e32 v[28:29], 0
	v_mov_b64_e32 v[30:31], 0
	v_mov_b64_e32 v[40:41], 0
	v_mov_b64_e32 v[42:43], 0
	v_mov_b64_e32 v[44:45], 0
	v_mov_b64_e32 v[46:47], 0
	v_mov_b64_e32 v[16:17], 0
	v_mov_b64_e32 v[18:19], 0
	v_mov_b64_e32 v[20:21], 0
	v_mov_b64_e32 v[22:23], 0
	v_mov_b64_e32 v[32:33], 0
	v_mov_b64_e32 v[34:35], 0
	v_mov_b64_e32 v[36:37], 0
	v_mov_b64_e32 v[38:39], 0
	v_mov_b64_e32 v[48:49], 0
	v_mov_b64_e32 v[50:51], 0
	v_mov_b64_e32 v[52:53], 0
	v_mov_b64_e32 v[54:55], 0
	v_mov_b64_e32 v[56:57], 0
	v_mov_b64_e32 v[58:59], 0
	v_mov_b64_e32 v[60:61], 0
	v_mov_b64_e32 v[62:63], 0
	v_mov_b64_e32 v[64:65], 0
	v_mov_b64_e32 v[66:67], 0
	v_mov_b64_e32 v[68:69], 0
	v_mov_b64_e32 v[70:71], 0
	v_mov_b64_e32 v[72:73], 0
	v_mov_b64_e32 v[74:75], 0
	v_mov_b64_e32 v[76:77], 0
	v_mov_b64_e32 v[78:79], 0
	v_mov_b64_e32 v[88:89], 0
	v_mov_b64_e32 v[90:91], 0
	v_mov_b64_e32 v[92:93], 0
	v_mov_b64_e32 v[94:95], 0
	v_mov_b64_e32 v[104:105], 0
	v_mov_b64_e32 v[106:107], 0
	v_mov_b64_e32 v[108:109], 0
	v_mov_b64_e32 v[110:111], 0
	v_mov_b64_e32 v[80:81], 0
	v_mov_b64_e32 v[82:83], 0
	v_mov_b64_e32 v[84:85], 0
	v_mov_b64_e32 v[86:87], 0
	v_mov_b64_e32 v[96:97], 0
	v_mov_b64_e32 v[98:99], 0
	v_mov_b64_e32 v[100:101], 0
	v_mov_b64_e32 v[102:103], 0
	v_mov_b64_e32 v[112:113], 0
	v_mov_b64_e32 v[114:115], 0
	v_mov_b64_e32 v[116:117], 0
	v_mov_b64_e32 v[118:119], 0
	v_mov_b64_e32 v[120:121], 0
	v_mov_b64_e32 v[122:123], 0
	v_mov_b64_e32 v[124:125], 0
	v_mov_b64_e32 v[126:127], 0

; template <class Epi>
; __device__ __forceinline__ void gemm_phase(LAS unsigned char* lds, const Gemm g, const Sched& S, const Epi& E) {
;     ...
;         const bool has_next = S.next(ui + 1, nxt);
;         const char* nA = has_next ? (const char*)g.A + (size_t)S.aoff(nxt) * 2 : cA; const char* nB = has_next ? (const char*)g.Bt + (size_t)S.boff(nxt) * 2 : cB;
;     ...
;         for (int a = 0; a < 2; ++a)
; #pragma unroll
;             for (int b = 0; b < 2; ++b)
; #pragma unroll
;                 for (int m = 0; m < 4; ++m)
; #pragma unroll
;                     for (int n = 0; n < 2; ++n) acc[a][b][m][n] = (f32x4){0.f, 0.f, 0.f, 0.f};
.LBB0_1730:
	s_ashr_i32 s17, s16, 31
	s_lshl_b64 s[18:19], s[16:17], 19
	s_add_u32 s18, s13, s18
	s_addc_u32 s19, s38, s19
	s_and_b64 s[20:21], s[8:9], exec
	s_cselect_b32 s17, s19, s27
	s_cselect_b32 s23, s18, s26
	s_ashr_i32 s15, s14, 31
	s_lshl_b64 s[20:21], s[14:15], 19
	s_add_u32 s20, s10, s20
	s_addc_u32 s21, s11, s21
	s_and_b64 s[36:37], s[8:9], exec
	s_cselect_b32 s15, s21, s29
	s_cselect_b32 s50, s20, s28
	s_add_u32 s26, s26, 0x40080
	s_addc_u32 s27, s27, 0
	s_add_u32 s51, s28, 0x100
	v_mov_b32_e32 v8, 0
	s_addc_u32 s52, s29, 0
	s_mov_b32 s53, -2
	v_mov_b32_e32 v9, 0
	v_mov_b64_e32 v[10:11], 0
	v_mov_b64_e32 v[0:1], 0
	v_mov_b64_e32 v[2:3], 0
	v_mov_b64_e32 v[24:25], 0
	v_mov_b64_e32 v[26:27], 0
	v_mov_b64_e32 v[16:17], 0
	v_mov_b64_e32 v[18:19], 0
	v_mov_b64_e32 v[40:41], 0
	v_mov_b64_e32 v[42:43], 0
	v_mov_b64_e32 v[32:33], 0
	v_mov_b64_e32 v[34:35], 0
	v_mov_b64_e32 v[56:57], 0
	v_mov_b64_e32 v[58:59], 0
	v_mov_b64_e32 v[48:49], 0
	v_mov_b64_e32 v[50:51], 0
	v_mov_b64_e32 v[12:13], 0
	v_mov_b64_e32 v[14:15], 0
	v_mov_b64_e32 v[4:5], 0
	v_mov_b64_e32 v[6:7], 0
	v_mov_b64_e32 v[28:29], 0
	v_mov_b64_e32 v[30:31], 0
	v_mov_b64_e32 v[20:21], 0
	v_mov_b64_e32 v[22:23], 0
	v_mov_b64_e32 v[44:45], 0
	v_mov_b64_e32 v[46:47], 0
	v_mov_b64_e32 v[36:37], 0
	v_mov_b64_e32 v[38:39], 0
	v_mov_b64_e32 v[60:61], 0
	v_mov_b64_e32 v[62:63], 0
	v_mov_b64_e32 v[52:53], 0
	v_mov_b64_e32 v[54:55], 0
	v_mov_b64_e32 v[72:73], 0
	v_mov_b64_e32 v[74:75], 0
	v_mov_b64_e32 v[64:65], 0
	v_mov_b64_e32 v[66:67], 0
	v_mov_b64_e32 v[88:89], 0
	v_mov_b64_e32 v[90:91], 0
	v_mov_b64_e32 v[80:81], 0
	v_mov_b64_e32 v[82:83], 0
	v_mov_b64_e32 v[104:105], 0
	v_mov_b64_e32 v[106:107], 0
	v_mov_b64_e32 v[96:97], 0
	v_mov_b64_e32 v[98:99], 0
	v_mov_b64_e32 v[120:121], 0
	v_mov_b64_e32 v[122:123], 0
	v_mov_b64_e32 v[112:113], 0
	v_mov_b64_e32 v[114:115], 0
	v_mov_b64_e32 v[76:77], 0
	v_mov_b64_e32 v[78:79], 0
	v_mov_b64_e32 v[68:69], 0
	v_mov_b64_e32 v[70:71], 0
	v_mov_b64_e32 v[92:93], 0
	v_mov_b64_e32 v[94:95], 0
	v_mov_b64_e32 v[84:85], 0
	v_mov_b64_e32 v[86:87], 0
	v_mov_b64_e32 v[108:109], 0
	v_mov_b64_e32 v[110:111], 0
	v_mov_b64_e32 v[100:101], 0
	v_mov_b64_e32 v[102:103], 0
	v_mov_b64_e32 v[124:125], 0
	v_mov_b64_e32 v[126:127], 0
	v_mov_b64_e32 v[116:117], 0
	v_mov_b64_e32 v[118:119], 0

; template <class Epi>
; __device__ __forceinline__ void gemm_phase(LAS unsigned char* lds, const Gemm g, const Sched& S, const Epi& E) {
;     ...
;     Unit cur, nxt; int ui = 0;
;     if (!S.next(0, cur)) return;
;     f32x4 acc[2][2][4][2];
; #pragma unroll
;     for (int a = 0; a < 2; ++a)
; #pragma unroll
;         for (int b = 0; b < 2; ++b)
; #pragma unroll
;             for (int m = 0; m < 4; ++m)
; #pragma unroll
;                 for (int n = 0; n < 2; ++n) acc[a][b][m][n] = (f32x4){0.f, 0.f, 0.f, 0.f};
;     bf16x8 At[4][2], B0[2][2], B1[2][2];
;     const char* cA = (const char*)g.A + (size_t)S.aoff(cur) * 2; const char* cB = (const char*)g.Bt + (size_t)S.boff(cur) * 2;
.LBB0_1833:
	v_mov_b32_e32 v0, 0
	s_mov_b32 s0, s60
	s_mov_b32 s13, s59
	v_mov_b32_e32 v1, 0
	v_mov_b64_e32 v[2:3], 0
	v_mov_b64_e32 v[4:5], 0
	v_mov_b64_e32 v[6:7], 0
	v_mov_b64_e32 v[16:17], 0
	v_mov_b64_e32 v[18:19], 0
	v_mov_b64_e32 v[20:21], 0
	v_mov_b64_e32 v[22:23], 0
	v_mov_b64_e32 v[32:33], 0
	v_mov_b64_e32 v[34:35], 0
	v_mov_b64_e32 v[36:37], 0
	v_mov_b64_e32 v[38:39], 0
	v_mov_b64_e32 v[48:49], 0
	v_mov_b64_e32 v[50:51], 0
	v_mov_b64_e32 v[52:53], 0
	v_mov_b64_e32 v[54:55], 0
	v_mov_b64_e32 v[8:9], 0
	v_mov_b64_e32 v[10:11], 0
	v_mov_b64_e32 v[12:13], 0
	v_mov_b64_e32 v[14:15], 0
	v_mov_b64_e32 v[24:25], 0
	v_mov_b64_e32 v[26:27], 0
	v_mov_b64_e32 v[28:29], 0
	v_mov_b64_e32 v[30:31], 0
	v_mov_b64_e32 v[40:41], 0
	v_mov_b64_e32 v[42:43], 0
	v_mov_b64_e32 v[44:45], 0
	v_mov_b64_e32 v[46:47], 0
	v_mov_b64_e32 v[56:57], 0
	v_mov_b64_e32 v[58:59], 0
	v_mov_b64_e32 v[60:61], 0
	v_mov_b64_e32 v[62:63], 0
	v_mov_b64_e32 v[64:65], 0
	v_mov_b64_e32 v[66:67], 0
	v_mov_b64_e32 v[68:69], 0
	v_mov_b64_e32 v[70:71], 0
	v_mov_b64_e32 v[80:81], 0
	v_mov_b64_e32 v[82:83], 0
	v_mov_b64_e32 v[84:85], 0
	v_mov_b64_e32 v[86:87], 0
	v_mov_b64_e32 v[96:97], 0
	v_mov_b64_e32 v[98:99], 0
	v_mov_b64_e32 v[100:101], 0
	v_mov_b64_e32 v[102:103], 0
	v_mov_b64_e32 v[112:113], 0
	v_mov_b64_e32 v[114:115], 0
	v_mov_b64_e32 v[116:117], 0
	v_mov_b64_e32 v[118:119], 0
	v_mov_b64_e32 v[72:73], 0
	v_mov_b64_e32 v[74:75], 0
	v_mov_b64_e32 v[76:77], 0
	v_mov_b64_e32 v[78:79], 0
	v_mov_b64_e32 v[88:89], 0
	v_mov_b64_e32 v[90:91], 0
	v_mov_b64_e32 v[92:93], 0
	v_mov_b64_e32 v[94:95], 0
	v_mov_b64_e32 v[104:105], 0
	v_mov_b64_e32 v[106:107], 0
	v_mov_b64_e32 v[108:109], 0
	v_mov_b64_e32 v[110:111], 0
	v_mov_b64_e32 v[120:121], 0
	v_mov_b64_e32 v[122:123], 0
	v_mov_b64_e32 v[124:125], 0
	v_mov_b64_e32 v[126:127], 0
	s_andn2_b64 vcc, exec, s[20:21]
	s_cbranch_vccnz .LBB0_1835
	s_branch .LBB0_1836
